# v55 + 176 filter tiles (2 per WG) in the idle third round of the even in-proj GEMM, 368 stay in k0
# speedup vs baseline: 1.0090x; 1.0090x over previous
.LBB0_475:
	s_waitcnt vmcnt(0)
	v_readlane_b32 s28, v255, 4
	v_readlane_b32 s36, v255, 6
	v_readlane_b32 s70, v255, 8
	v_readlane_b32 s74, v255, 10
	v_readlane_b32 s29, v255, 5
	v_readlane_b32 s37, v255, 7
	v_readlane_b32 s71, v255, 9
	v_readlane_b32 s75, v255, 11
	s_mov_b32 s34, 0xc200000
	s_barrier
	s_cmp_eq_u32 s56, 0x100
	s_cbranch_scc0 .LBB0_476
	s_cmp_lt_u32 s96, 0xa8
	s_cbranch_scc1 .LBB0_476
	s_mov_b64 s[0:1], s[72:73]
	s_load_dwordx2 s[64:65], s[72:73], 0x120
	s_add_i32 s101, s96, 0xc8
	s_movk_i32 s98, 0x58
	s_movk_i32 s99, 0x21f
	s_waitcnt lgkmcnt(0)
	s_branch .Lkt_entry
	s_nop 0

.LBB0_562:
	v_readlane_b32 s2, v253, 16
	v_readlane_b32 s6, v255, 22
	v_readlane_b32 s3, v253, 17
	v_readlane_b32 s7, v255, 23
	s_or_b64 s[2:3], s[6:7], s[2:3]
	s_and_b64 vcc, exec, s[2:3]
	s_cbranch_vccnz .LBB0_567
	s_mov_b32 s101, s96
	s_mov_b32 s98, s56
	s_movk_i32 s99, 0x21f
	s_cmp_eq_u32 s56, 0x100
	s_cbranch_scc0 .Lkt_entry
	s_movk_i32 s99, 0x16f
	s_nop 0
